# attention max phase: drop 3 redundant canonicalising v_max (x,x,x) on top of the single-add row-sum change
# baseline (speedup 1.0000x reference)
.LBB0_1797:
	s_bitcmp1_b32 s10, 0
	s_cselect_b32 s10, 0x5800, 0
	s_add_i32 s56, s10, 0
	v_add3_u32 v0, s56, v204, v205
	ds_read_b128 v[50:53], v0
	ds_read_b128 v[178:181], v0 offset:32
	ds_read_b128 v[182:185], v0 offset:6656
	ds_read_b128 v[186:189], v0 offset:6688
	s_waitcnt lgkmcnt(3)
	v_mfma_f32_32x32x16_bf16 v[66:81], v[50:53], v[82:85], v[34:49]
	s_waitcnt lgkmcnt(1)
	v_mfma_f32_32x32x16_bf16 v[50:65], v[182:185], v[82:85], v[34:49]
	v_mfma_f32_32x32x16_bf16 v[66:81], v[178:181], v[86:89], v[66:81]
	ds_read_b128 v[178:181], v0 offset:64
	ds_read_b128 v[182:185], v0 offset:96
	s_waitcnt lgkmcnt(2)
	v_mfma_f32_32x32x16_bf16 v[50:65], v[186:189], v[86:89], v[50:65]
	s_waitcnt lgkmcnt(1)
	v_mfma_f32_32x32x16_bf16 v[66:81], v[178:181], v[90:93], v[66:81]
	ds_read_b128 v[178:181], v0 offset:6720
	ds_read_b128 v[186:189], v0 offset:6752
	s_waitcnt lgkmcnt(1)
	v_mfma_f32_32x32x16_bf16 v[50:65], v[178:181], v[90:93], v[50:65]
	v_mfma_f32_32x32x16_bf16 v[66:81], v[182:185], v[94:97], v[66:81]
	ds_read_b128 v[178:181], v0 offset:128
	ds_read_b128 v[182:185], v0 offset:160
	s_waitcnt lgkmcnt(2)
	v_mfma_f32_32x32x16_bf16 v[50:65], v[186:189], v[94:97], v[50:65]
	s_waitcnt lgkmcnt(1)
	v_mfma_f32_32x32x16_bf16 v[66:81], v[178:181], v[98:101], v[66:81]
	ds_read_b128 v[178:181], v0 offset:6784
	ds_read_b128 v[186:189], v0 offset:6816
	s_waitcnt lgkmcnt(1)
	v_mfma_f32_32x32x16_bf16 v[50:65], v[178:181], v[98:101], v[50:65]
	v_mfma_f32_32x32x16_bf16 v[66:81], v[182:185], v[102:105], v[66:81]
	s_waitcnt lgkmcnt(0)
	v_mfma_f32_32x32x16_bf16 v[50:65], v[186:189], v[102:105], v[50:65]
	s_nop 15
	s_nop 7
	s_nop 0
	v_max3_f32 v0, v66, v67, v50
	v_max3_f32 v178, v68, v69, v51
	s_nop 0
	v_max3_f32 v0, v0, v52, v53
	v_max3_f32 v178, v178, v72, v73
	s_nop 0
	v_max3_f32 v0, v0, v70, v71
	v_max3_f32 v178, v178, v56, v57
	s_nop 0
	v_max3_f32 v0, v0, v54, v55
	v_max3_f32 v178, v178, v76, v77
	s_nop 0
	v_max3_f32 v0, v0, v74, v75
	v_max3_f32 v178, v178, v60, v61
	s_nop 0
	v_max3_f32 v0, v0, v58, v59
	v_max3_f32 v178, v178, v80, v81
	s_nop 0
	v_max3_f32 v0, v0, v78, v79
	v_max3_f32 v178, v178, v64, v65
	s_nop 0
	v_max3_f32 v0, v0, v62, v63
	v_max_f32_e32 v0, v0, v178
	ds_bpermute_b32 v178, v206, v0
	s_waitcnt lgkmcnt(0)
	v_max_f32_e32 v0, v0, v178
	v_cmp_lt_f32_e32 vcc, 0x41000000, v0
	s_cbranch_vccz .LBB0_1801
	v_max_f32_e32 v0, v0, v0
	v_max_f32_e32 v0, 0, v0
	v_exp_f32_e64 v225, -v0
	s_and_saveexec_b64 s[10:11], s[6:7]
	ds_write_b32 v207, v225 offset:45056
	s_or_b64 exec, exec, s[10:11]
	v_add_f32_e32 v173, v173, v0
	v_pk_add_f32 v[66:67], v[66:67], v[0:1] op_sel_hi:[1,0] neg_lo:[0,1] neg_hi:[0,1]
	v_pk_add_f32 v[50:51], v[50:51], v[0:1] op_sel_hi:[1,0] neg_lo:[0,1] neg_hi:[0,1]
	v_pk_add_f32 v[68:69], v[68:69], v[0:1] op_sel_hi:[1,0] neg_lo:[0,1] neg_hi:[0,1]
	v_pk_add_f32 v[52:53], v[52:53], v[0:1] op_sel_hi:[1,0] neg_lo:[0,1] neg_hi:[0,1]
	v_pk_add_f32 v[70:71], v[70:71], v[0:1] op_sel_hi:[1,0] neg_lo:[0,1] neg_hi:[0,1]
	v_pk_add_f32 v[54:55], v[54:55], v[0:1] op_sel_hi:[1,0] neg_lo:[0,1] neg_hi:[0,1]
	v_pk_add_f32 v[72:73], v[72:73], v[0:1] op_sel_hi:[1,0] neg_lo:[0,1] neg_hi:[0,1]
	v_pk_add_f32 v[56:57], v[56:57], v[0:1] op_sel_hi:[1,0] neg_lo:[0,1] neg_hi:[0,1]
	v_pk_add_f32 v[74:75], v[74:75], v[0:1] op_sel_hi:[1,0] neg_lo:[0,1] neg_hi:[0,1]
	v_pk_add_f32 v[58:59], v[58:59], v[0:1] op_sel_hi:[1,0] neg_lo:[0,1] neg_hi:[0,1]
	v_pk_add_f32 v[76:77], v[76:77], v[0:1] op_sel_hi:[1,0] neg_lo:[0,1] neg_hi:[0,1]
	v_pk_add_f32 v[60:61], v[60:61], v[0:1] op_sel_hi:[1,0] neg_lo:[0,1] neg_hi:[0,1]
	v_pk_add_f32 v[78:79], v[78:79], v[0:1] op_sel_hi:[1,0] neg_lo:[0,1] neg_hi:[0,1]
	v_pk_add_f32 v[62:63], v[62:63], v[0:1] op_sel_hi:[1,0] neg_lo:[0,1] neg_hi:[0,1]
	v_pk_add_f32 v[80:81], v[80:81], v[0:1] op_sel_hi:[1,0] neg_lo:[0,1] neg_hi:[0,1]
	v_pk_add_f32 v[64:65], v[64:65], v[0:1] op_sel_hi:[1,0] neg_lo:[0,1] neg_hi:[0,1]
	s_waitcnt lgkmcnt(0)
	v_add_u32_e32 v0, s50, v205
	ds_read_b128 v[178:181], v0 offset:45120
	ds_read_b128 v[182:185], v0 offset:45152
	ds_read_b128 v[186:189], v0 offset:45056
	ds_read_b128 v[190:193], v0 offset:45088
	v_xor_b32_e32 v34, 0x80000000, v173
	v_mov_b32_e32 v35, v34
	v_mov_b32_e32 v36, v34
	v_mov_b32_e32 v37, v34
	v_mov_b32_e32 v38, v34
	v_mov_b32_e32 v39, v34
	v_mov_b32_e32 v40, v34
	v_mov_b32_e32 v41, v34
	v_mov_b32_e32 v42, v34
	v_mov_b32_e32 v43, v34
	v_mov_b32_e32 v44, v34
	v_mov_b32_e32 v45, v34
	v_mov_b32_e32 v46, v34
	v_mov_b32_e32 v47, v34
	v_mov_b32_e32 v48, v34
	v_mov_b32_e32 v49, v34
	v_mul_f32_e32 v224, v224, v225
	s_waitcnt lgkmcnt(2)
	v_pk_mul_f32 v[30:31], v[30:31], v[182:183]
	v_pk_mul_f32 v[26:27], v[26:27], v[178:179]
	s_waitcnt lgkmcnt(0)
	v_pk_mul_f32 v[22:23], v[22:23], v[190:191]
	v_pk_mul_f32 v[32:33], v[32:33], v[184:185]
	v_pk_mul_f32 v[28:29], v[28:29], v[180:181]
	v_pk_mul_f32 v[24:25], v[24:25], v[192:193]
	v_pk_mul_f32 v[20:21], v[20:21], v[188:189]
	v_pk_mul_f32 v[18:19], v[18:19], v[186:187]
	v_pk_mul_f32 v[14:15], v[14:15], v[182:183]
	v_pk_mul_f32 v[10:11], v[10:11], v[178:179]
	v_pk_mul_f32 v[6:7], v[6:7], v[190:191]
	v_pk_mul_f32 v[16:17], v[16:17], v[184:185]
	v_pk_mul_f32 v[12:13], v[12:13], v[180:181]
	v_pk_mul_f32 v[8:9], v[8:9], v[192:193]
	v_pk_mul_f32 v[4:5], v[4:5], v[188:189]
	v_pk_mul_f32 v[2:3], v[2:3], v[186:187]
